# scan: first-batch k^T fragment ds_reads hoisted above the rotary write block (v^T reads after it), on top of r1+r3lite K-loop, widened ret_out stores and ret_out L2 prefetch
# baseline (speedup 1.0000x reference)
; #define SCAN_STORE(st) do { \
;             bf16_t* sp = states + ((size_t)((bh * 2 + dir) * 32 + SCAN_NCH(st))) * 16384 + (64 * half + 16 * et + fr) * 128 + 16 * dbase + 4 * fq; \
;             _Pragma("unroll") for (int dt = 0; dt < 4; ++dt) { u32x2 w; w.x = cvt_pk_bf16(acc[dt][0], acc[dt][1]); w.y = cvt_pk_bf16(acc[dt][2], acc[dt][3]); *(u32x2*)(sp + 16 * dt) = w; } } while (0)
; #define SCAN_BAR() do { asm volatile("s_waitcnt lgkmcnt(0)" ::: "memory"); __builtin_amdgcn_s_barrier(); asm volatile("" ::: "memory"); } while (0)
; __device__ __forceinline__ void ret_scan(const bf16_t* proj, const float* cosT, const float* sinT, const float* decay, bf16_t* states, unsigned char* lds, int tid, int bx) {
;     ...
;         for (int step = 0; step < 30; step += 2) {
;             SCAN_STORE(step);
; #pragma unroll
;             for (int dt = 0; dt < 4; ++dt) acc[dt] *= cdec;
;             SCAN_WRITE(B, 1); if (step + 3 <= 30) SCAN_LOAD(B, SCAN_NCH(step + 3));
;             SCAN_MMA(0);
;             SCAN_BAR();
;             SCAN_STORE(step + 1);
; #pragma unroll
;             for (int dt = 0; dt < 4; ++dt) acc[dt] *= cdec;
;             SCAN_WRITE(A, 0); if (step + 4 <= 30) SCAN_LOAD(A, SCAN_NCH(step + 4));
;             SCAN_MMA(1);
.LBB0_200:
	v_pk_mul_f32 v[126:127], v[128:129], v[126:127]
	v_pk_mul_f32 v[124:125], v[130:131], v[124:125]
	v_pk_mul_f32 v[122:123], v[128:129], v[122:123]
	v_pk_mul_f32 v[120:121], v[130:131], v[120:121]
	v_pk_mul_f32 v[118:119], v[128:129], v[118:119]
	v_pk_mul_f32 v[116:117], v[130:131], v[116:117]
	v_pk_mul_f32 v[58:59], v[128:129], v[58:59]
	v_pk_mul_f32 v[56:57], v[130:131], v[56:57]
	s_setprio 1
	s_waitcnt lgkmcnt(0)
	v_mfma_f32_16x16x32_bf16 v[124:127], v[208:211], v[148:151], v[124:127]
	s_waitcnt lgkmcnt(7)
	v_mfma_f32_16x16x32_bf16 v[120:123], v[212:215], v[148:151], v[120:123]
	s_waitcnt lgkmcnt(6)
	v_mfma_f32_16x16x32_bf16 v[116:119], v[216:219], v[148:151], v[116:119]
	s_waitcnt lgkmcnt(5)
	v_mfma_f32_16x16x32_bf16 v[56:59], v[220:223], v[148:151], v[56:59]
	s_waitcnt lgkmcnt(3)
	v_mfma_f32_16x16x32_bf16 v[124:127], v[228:231], v[224:227], v[124:127]
	s_waitcnt lgkmcnt(2)
	v_mfma_f32_16x16x32_bf16 v[120:123], v[232:235], v[224:227], v[120:123]
	s_waitcnt lgkmcnt(1)
	v_mfma_f32_16x16x32_bf16 v[116:119], v[236:239], v[224:227], v[116:119]
	s_waitcnt lgkmcnt(0)
	v_mfma_f32_16x16x32_bf16 v[56:59], v[240:243], v[224:227], v[56:59]
	s_setprio 0
	ds_read_b128 v[148:151], v198 offset:52224
	ds_read_b128 v[208:211], v198 offset:60928
	ds_read_b128 v[212:215], v199 offset:56576
	ds_read_b128 v[216:219], v199 offset:65280
	ds_read_b128 v[220:223], v205
	ds_read_b128 v[224:227], v206
	ds_read_b128 v[228:231], v201 offset:52224
	ds_read_b128 v[232:235], v201 offset:60928
	ds_read_b128 v[236:239], v202 offset:56576
	ds_read_b128 v[240:243], v202 offset:65280
	s_setprio 1
	s_waitcnt lgkmcnt(5)
	v_mfma_f32_16x16x32_bf16 v[124:127], v[148:151], v[220:223], v[124:127]
	v_mfma_f32_16x16x32_bf16 v[120:123], v[212:215], v[220:223], v[120:123]
	v_mfma_f32_16x16x32_bf16 v[148:151], v[208:211], v[220:223], v[116:119]
	v_mfma_f32_16x16x32_bf16 v[208:211], v[216:219], v[220:223], v[56:59]
	s_waitcnt lgkmcnt(3)
	v_mfma_f32_16x16x32_bf16 v[56:59], v[228:231], v[224:227], v[124:127]
	s_waitcnt lgkmcnt(1)
	v_mfma_f32_16x16x32_bf16 v[116:119], v[236:239], v[224:227], v[120:123]
	v_mfma_f32_16x16x32_bf16 v[120:123], v[232:235], v[224:227], v[148:151]
	s_waitcnt lgkmcnt(0)
	v_mfma_f32_16x16x32_bf16 v[124:127], v[240:243], v[224:227], v[208:211]
	s_setprio 0
	s_waitcnt lgkmcnt(0)
	s_barrier
	s_add_i32 s34, s34, 2
	s_add_i32 s35, s35, -2
	s_cmp_gt_u32 s38, 27
	s_cbranch_scc1 .LBB0_196
.LBB0_201:
	s_add_i32 s38, s34, -4
	s_add_i32 s6, s35, 4
	s_and_b64 s[0:1], s[36:37], exec
	s_cselect_b32 s0, s38, s6
	s_or_b32 s0, s0, s31
	s_ashr_i32 s1, s0, 31
	s_lshl_b64 s[0:1], s[0:1], 15
	v_lshl_add_u64 v[136:137], v[134:135], 0, s[0:1]
	v_cvt_pk_bf16_f32 v144, v56, v57
	v_cvt_pk_bf16_f32 v145, v58, v59
	global_store_dwordx2 v[136:137], v[144:145], off
	v_cvt_pk_bf16_f32 v144, v116, v117
	v_cvt_pk_bf16_f32 v145, v118, v119
	global_store_dwordx2 v[136:137], v[144:145], off offset:32
	v_cvt_pk_bf16_f32 v144, v120, v121
	v_cvt_pk_bf16_f32 v145, v122, v123
	global_store_dwordx2 v[136:137], v[144:145], off offset:64
	v_cvt_pk_bf16_f32 v144, v124, v125
	v_cvt_pk_bf16_f32 v145, v126, v127
	global_store_dwordx2 v[136:137], v[144:145], off offset:96
	ds_read_b128 v[208:211], v192
	ds_read_b128 v[212:215], v193 offset:4352
	ds_read_b128 v[216:219], v192 offset:8704
	ds_read_b128 v[220:223], v193 offset:13056
	ds_read_b128 v[228:231], v195
	ds_read_b128 v[232:235], v196 offset:4352
	ds_read_b128 v[236:239], v195 offset:8704
	ds_read_b128 v[240:243], v196 offset:13056
	s_waitcnt vmcnt(28)
	v_lshlrev_b32_e32 v145, 16, v12
	v_lshlrev_b32_e32 v144, 16, v4
	s_waitcnt vmcnt(24)
	v_mov_b32_e32 v148, v28
	s_waitcnt vmcnt(10)
	v_mov_b32_e32 v149, v44
	v_mov_b32_e32 v150, v36
	s_waitcnt vmcnt(8)
	v_mov_b32_e32 v151, v52
	v_lshlrev_b32_e32 v137, 16, v8
	v_lshlrev_b32_e32 v136, 16, v0
	v_pk_mul_f32 v[152:153], v[150:151], v[144:145]
	v_pk_mul_f32 v[144:145], v[148:149], v[144:145]
	v_pk_fma_f32 v[152:153], v[148:149], v[136:137], v[152:153] neg_lo:[0,0,1] neg_hi:[0,0,1]
	v_pk_fma_f32 v[136:137], v[150:151], v[136:137], v[144:145]
	v_and_b32_e32 v145, 0xffff0000, v12
	v_cvt_pk_bf16_f32 v141, v136, v137
	v_lshlrev_b32_e32 v137, 16, v20
	v_lshlrev_b32_e32 v136, 16, v16
	v_pk_mul_f32 v[136:137], v[170:171], v[136:137]
	v_and_b32_e32 v144, 0xffff0000, v4
	v_mov_b32_e32 v150, v37
	v_mov_b32_e32 v151, v53
	v_cvt_pk_bf16_f32 v129, v152, v153
	v_cvt_pk_bf16_f32 v143, v136, v137
	v_and_b32_e32 v137, 0xffff0000, v8
	v_and_b32_e32 v136, 0xffff0000, v0
	v_mov_b32_e32 v148, v29
	v_mov_b32_e32 v149, v45
	v_pk_mul_f32 v[152:153], v[150:151], v[144:145]
	v_pk_mul_f32 v[144:145], v[148:149], v[144:145]
	v_pk_fma_f32 v[152:153], v[148:149], v[136:137], v[152:153] neg_lo:[0,0,1] neg_hi:[0,0,1]
	v_pk_fma_f32 v[136:137], v[150:151], v[136:137], v[144:145]
	v_cvt_pk_bf16_f32 v147, v152, v153
	ds_write2_b32 v189, v129, v147 offset1:68
	v_cvt_pk_bf16_f32 v129, v136, v137
	v_and_b32_e32 v137, 0xffff0000, v20
	v_and_b32_e32 v136, 0xffff0000, v16
	v_add_u32_e32 v147, 0x4400, v189
	v_pk_mul_f32 v[136:137], v[170:171], v[136:137]
	v_lshlrev_b32_e32 v145, 16, v13
	v_lshlrev_b32_e32 v144, 16, v5
	v_mov_b32_e32 v148, v30
	v_mov_b32_e32 v149, v46
	v_mov_b32_e32 v150, v38
	v_mov_b32_e32 v151, v54
	ds_write2_b32 v147, v141, v129 offset1:68
	v_cvt_pk_bf16_f32 v129, v136, v137
	v_lshlrev_b32_e32 v137, 16, v9
	v_lshlrev_b32_e32 v136, 16, v1
	v_pk_mul_f32 v[152:153], v[150:151], v[144:145]
	v_pk_mul_f32 v[144:145], v[148:149], v[144:145]
	v_pk_fma_f32 v[152:153], v[148:149], v[136:137], v[152:153] neg_lo:[0,0,1] neg_hi:[0,0,1]
	v_pk_fma_f32 v[136:137], v[150:151], v[136:137], v[144:145]
	v_and_b32_e32 v145, 0xffff0000, v13
	v_cvt_pk_bf16_f32 v141, v136, v137
	v_lshlrev_b32_e32 v137, 16, v21
	v_lshlrev_b32_e32 v136, 16, v17
	v_pk_mul_f32 v[136:137], v[170:171], v[136:137]
	v_and_b32_e32 v144, 0xffff0000, v5
	v_mov_b32_e32 v150, v39
	v_mov_b32_e32 v151, v55
	ds_write2_b32 v190, v143, v129 offset1:68
	v_cvt_pk_bf16_f32 v129, v152, v153
	v_cvt_pk_bf16_f32 v143, v136, v137
	v_and_b32_e32 v137, 0xffff0000, v9
	v_and_b32_e32 v136, 0xffff0000, v1
	v_mov_b32_e32 v148, v31
	v_mov_b32_e32 v149, v47
	v_pk_mul_f32 v[152:153], v[150:151], v[144:145]
	v_pk_mul_f32 v[144:145], v[148:149], v[144:145]
	v_pk_fma_f32 v[152:153], v[148:149], v[136:137], v[152:153] neg_lo:[0,0,1] neg_hi:[0,0,1]
	v_pk_fma_f32 v[136:137], v[150:151], v[136:137], v[144:145]
	v_cvt_pk_bf16_f32 v152, v152, v153
	ds_write2_b32 v189, v129, v152 offset0:136 offset1:204
	v_cvt_pk_bf16_f32 v129, v136, v137
	v_and_b32_e32 v137, 0xffff0000, v21
	v_and_b32_e32 v136, 0xffff0000, v17
	v_pk_mul_f32 v[136:137], v[170:171], v[136:137]
	v_lshlrev_b32_e32 v145, 16, v14
	v_lshlrev_b32_e32 v144, 16, v6
	v_mov_b32_e32 v148, v24
	v_mov_b32_e32 v149, v40
	v_mov_b32_e32 v150, v32
	v_mov_b32_e32 v151, v48
	ds_write2_b32 v147, v141, v129 offset0:136 offset1:204
	v_cvt_pk_bf16_f32 v129, v136, v137
	v_lshlrev_b32_e32 v137, 16, v10
	v_lshlrev_b32_e32 v136, 16, v2
	v_pk_mul_f32 v[152:153], v[150:151], v[144:145]
	v_pk_mul_f32 v[144:145], v[148:149], v[144:145]
	v_pk_fma_f32 v[152:153], v[148:149], v[136:137], v[152:153] neg_lo:[0,0,1] neg_hi:[0,0,1]
	v_pk_fma_f32 v[136:137], v[150:151], v[136:137], v[144:145]
	v_and_b32_e32 v145, 0xffff0000, v14
	v_cvt_pk_bf16_f32 v141, v136, v137
	v_lshlrev_b32_e32 v137, 16, v22
	v_lshlrev_b32_e32 v136, 16, v18
	v_pk_mul_f32 v[136:137], v[170:171], v[136:137]
	v_and_b32_e32 v144, 0xffff0000, v6
	v_mov_b32_e32 v150, v33
	v_mov_b32_e32 v151, v49
	ds_write2_b32 v190, v143, v129 offset0:136 offset1:204
	v_cvt_pk_bf16_f32 v129, v152, v153
	v_cvt_pk_bf16_f32 v143, v136, v137
	v_and_b32_e32 v137, 0xffff0000, v10
	v_and_b32_e32 v136, 0xffff0000, v2
	v_mov_b32_e32 v148, v25
	v_mov_b32_e32 v149, v41
	v_pk_mul_f32 v[152:153], v[150:151], v[144:145]
	v_pk_mul_f32 v[144:145], v[148:149], v[144:145]
	v_pk_fma_f32 v[152:153], v[148:149], v[136:137], v[152:153] neg_lo:[0,0,1] neg_hi:[0,0,1]
	v_add_u32_e32 v167, 0xd000, v187
	v_cvt_pk_bf16_f32 v147, v152, v153
	v_pk_fma_f32 v[136:137], v[150:151], v[136:137], v[144:145]
	ds_write2_b32 v167, v129, v147 offset0:16 offset1:84
	v_cvt_pk_bf16_f32 v129, v136, v137
	v_and_b32_e32 v137, 0xffff0000, v22
	v_and_b32_e32 v136, 0xffff0000, v18
	v_add_u32_e32 v147, 0x4800, v189
	v_pk_mul_f32 v[136:137], v[170:171], v[136:137]
	v_lshlrev_b32_e32 v145, 16, v15
	v_lshlrev_b32_e32 v144, 16, v7
	v_mov_b32_e32 v148, v26
	v_mov_b32_e32 v149, v42
	v_mov_b32_e32 v150, v34
	v_mov_b32_e32 v151, v50
	ds_write2_b32 v147, v141, v129 offset0:16 offset1:84
	v_cvt_pk_bf16_f32 v129, v136, v137
	v_lshlrev_b32_e32 v137, 16, v11
	v_lshlrev_b32_e32 v136, 16, v3
	v_pk_mul_f32 v[152:153], v[150:151], v[144:145]
	v_pk_mul_f32 v[144:145], v[148:149], v[144:145]
	v_add_u32_e32 v141, 0x400, v190
	v_pk_fma_f32 v[152:153], v[148:149], v[136:137], v[152:153] neg_lo:[0,0,1] neg_hi:[0,0,1]
	v_pk_fma_f32 v[136:137], v[150:151], v[136:137], v[144:145]
	ds_write2_b32 v141, v143, v129 offset0:16 offset1:84
	v_cvt_pk_bf16_f32 v143, v136, v137
	v_lshlrev_b32_e32 v137, 16, v23
	v_lshlrev_b32_e32 v136, 16, v19
	v_pk_mul_f32 v[136:137], v[170:171], v[136:137]
	v_and_b32_e32 v145, 0xffff0000, v15
	v_and_b32_e32 v144, 0xffff0000, v7
	v_mov_b32_e32 v150, v35
	v_mov_b32_e32 v151, v51
	v_cvt_pk_bf16_f32 v129, v152, v153
	v_cvt_pk_bf16_f32 v169, v136, v137
	v_and_b32_e32 v137, 0xffff0000, v11
	v_and_b32_e32 v136, 0xffff0000, v3
	v_mov_b32_e32 v148, v27
	v_mov_b32_e32 v149, v43
	v_pk_mul_f32 v[152:153], v[150:151], v[144:145]
	v_pk_mul_f32 v[144:145], v[148:149], v[144:145]
	v_pk_fma_f32 v[152:153], v[148:149], v[136:137], v[152:153] neg_lo:[0,0,1] neg_hi:[0,0,1]
	v_pk_fma_f32 v[136:137], v[150:151], v[136:137], v[144:145]
	v_cvt_pk_bf16_f32 v152, v152, v153
	ds_write2_b32 v167, v129, v152 offset0:152 offset1:220
	v_cvt_pk_bf16_f32 v129, v136, v137
	v_and_b32_e32 v137, 0xffff0000, v23
	v_and_b32_e32 v136, 0xffff0000, v19
	v_pk_mul_f32 v[136:137], v[170:171], v[136:137]
	ds_write2_b32 v147, v143, v129 offset0:152 offset1:220
	v_cvt_pk_bf16_f32 v129, v136, v137
	s_cmp_gt_u32 s38, 27
	ds_write2_b32 v141, v169, v129 offset0:152 offset1:220
	ds_read_b128 v[148:151], v191 offset:34816
	ds_read_b128 v[224:227], v194 offset:34816
	s_cbranch_scc1 .LBB0_203
	s_add_i32 s6, s34, -1
	s_add_i32 s17, s35, 1
	s_and_b64 s[0:1], s[36:37], exec
	s_cselect_b32 s0, s6, s17
	v_lshl_add_u32 v24, s0, 7, v183
	v_add_u32_e32 v2, s29, v24
	v_mov_b64_e32 v[0:1], s[14:15]
	v_mad_i64_i32 v[16:17], s[0:1], v2, s59, v[0:1]
	v_lshl_add_u64 v[8:9], v[16:17], 0, v[154:155]
	s_lshl_b32 s6, s30, 1
	v_add_co_u32_e32 v12, vcc, 0x2000, v8
	v_lshl_add_u64 v[16:17], v[16:17], 0, s[6:7]
	v_lshlrev_b32_e32 v24, 6, v24
	v_addc_co_u32_e32 v13, vcc, 0, v9, vcc
	v_lshl_add_u64 v[16:17], v[16:17], 0, v[154:155]
	v_ashrrev_i32_e32 v25, 31, v24
	v_add_co_u32_e32 v20, vcc, 0x2000, v16
	v_lshlrev_b64 v[24:25], 2, v[24:25]
	s_nop 0
	v_addc_co_u32_e32 v21, vcc, 0, v17, vcc
	v_lshl_add_u64 v[44:45], v[160:161], 0, v[24:25]
	v_lshl_add_u64 v[52:53], v[162:163], 0, v[24:25]
	global_load_dwordx4 v[0:3], v[8:9], off offset:1536
	global_load_dwordx4 v[4:7], v[8:9], off offset:1664
	s_nop 0
	global_load_dwordx4 v[8:11], v[12:13], off
	s_nop 0
	global_load_dwordx4 v[12:15], v[12:13], off offset:128
	s_nop 0
	global_load_dwordx4 v[16:19], v[16:17], off offset:3072
	s_nop 0
	global_load_dwordx4 v[20:23], v[20:21], off offset:1536
	s_nop 0
	global_load_dwordx4 v[24:27], v[44:45], off offset:16
	global_load_dwordx4 v[28:31], v[44:45], off
	global_load_dwordx4 v[32:35], v[52:53], off offset:16
	global_load_dwordx4 v[36:39], v[52:53], off
	global_load_dwordx4 v[40:43], v[44:45], off offset:272
	s_nop 0
	global_load_dwordx4 v[44:47], v[44:45], off offset:256
	s_nop 0
	global_load_dwordx4 v[48:51], v[52:53], off offset:272
	s_nop 0
	global_load_dwordx4 v[52:55], v[52:53], off offset:256
; #define SCAN_STORE(st) do { \
;             bf16_t* sp = states + ((size_t)((bh * 2 + dir) * 32 + SCAN_NCH(st))) * 16384 + (64 * half + 16 * et + fr) * 128 + 16 * dbase + 4 * fq; \
;             _Pragma("unroll") for (int dt = 0; dt < 4; ++dt) { u32x2 w; w.x = cvt_pk_bf16(acc[dt][0], acc[dt][1]); w.y = cvt_pk_bf16(acc[dt][2], acc[dt][3]); *(u32x2*)(sp + 16 * dt) = w; } } while (0)
; #define SCAN_BAR() do { asm volatile("s_waitcnt lgkmcnt(0)" ::: "memory"); __builtin_amdgcn_s_barrier(); asm volatile("" ::: "memory"); } while (0)
; __device__ __forceinline__ void ret_scan(const bf16_t* proj, const float* cosT, const float* sinT, const float* decay, bf16_t* states, unsigned char* lds, int tid, int bx) {
;     ...
;         SCAN_LOAD(A, SCAN_NCH(0)); SCAN_LOAD(B, SCAN_NCH(1));
;         SCAN_WRITE(A, 0);
;         SCAN_LOAD(A, SCAN_NCH(2));
;         SCAN_BAR();
;         for (int step = 0; step < 30; step += 2) {
;             SCAN_STORE(step);
; #pragma unroll
;             for (int dt = 0; dt < 4; ++dt) acc[dt] *= cdec;
;             SCAN_WRITE(B, 1); if (step + 3 <= 30) SCAN_LOAD(B, SCAN_NCH(step + 3));
;             SCAN_MMA(0);
;             SCAN_BAR();
;             SCAN_STORE(step + 1);
; #pragma unroll
;             for (int dt = 0; dt < 4; ++dt) acc[dt] *= cdec;
;             SCAN_WRITE(A, 0); if (step + 4 <= 30) SCAN_LOAD(A, SCAN_NCH(step + 4));
.LBB0_203:
	v_mov_b32_e32 v129, v128
	v_pk_mul_f32 v[58:59], v[128:129], v[58:59]
	v_pk_mul_f32 v[56:57], v[130:131], v[56:57]
	v_pk_mul_f32 v[118:119], v[128:129], v[118:119]
	v_pk_mul_f32 v[116:117], v[130:131], v[116:117]
	v_pk_mul_f32 v[122:123], v[128:129], v[122:123]
	v_pk_mul_f32 v[120:121], v[130:131], v[120:121]
	v_pk_mul_f32 v[126:127], v[128:129], v[126:127]
	v_pk_mul_f32 v[124:125], v[130:131], v[124:125]
	s_setprio 1
	s_waitcnt lgkmcnt(0)
	v_mfma_f32_16x16x32_bf16 v[56:59], v[208:211], v[148:151], v[56:59]
	s_waitcnt lgkmcnt(7)
	v_mfma_f32_16x16x32_bf16 v[116:119], v[212:215], v[148:151], v[116:119]
	s_waitcnt lgkmcnt(6)
	v_mfma_f32_16x16x32_bf16 v[120:123], v[216:219], v[148:151], v[120:123]
	s_waitcnt lgkmcnt(5)
	v_mfma_f32_16x16x32_bf16 v[124:127], v[220:223], v[148:151], v[124:127]
	s_waitcnt lgkmcnt(3)
	v_mfma_f32_16x16x32_bf16 v[56:59], v[228:231], v[224:227], v[56:59]
	s_waitcnt lgkmcnt(2)
	v_mfma_f32_16x16x32_bf16 v[116:119], v[232:235], v[224:227], v[116:119]
	s_waitcnt lgkmcnt(1)
	v_mfma_f32_16x16x32_bf16 v[120:123], v[236:239], v[224:227], v[120:123]
	s_waitcnt lgkmcnt(0)
	v_mfma_f32_16x16x32_bf16 v[124:127], v[240:243], v[224:227], v[124:127]
	s_setprio 0
	ds_read_b128 v[148:151], v197 offset:34816
	ds_read_b128 v[208:211], v198
	ds_read_b128 v[212:215], v199 offset:4352
	ds_read_b128 v[216:219], v198 offset:8704
	ds_read_b128 v[220:223], v199 offset:13056
	ds_read_b128 v[224:227], v200 offset:34816
	ds_read_b128 v[228:231], v201
	ds_read_b128 v[232:235], v201 offset:8704
	ds_read_b128 v[236:239], v202 offset:4352
	ds_read_b128 v[240:243], v202 offset:13056
	s_setprio 1
	s_waitcnt lgkmcnt(8)
	v_mfma_f32_16x16x32_bf16 v[56:59], v[208:211], v[148:151], v[56:59]
	s_waitcnt lgkmcnt(7)
	v_mfma_f32_16x16x32_bf16 v[116:119], v[212:215], v[148:151], v[116:119]
	s_waitcnt lgkmcnt(6)
	v_mfma_f32_16x16x32_bf16 v[208:211], v[216:219], v[148:151], v[120:123]
	s_waitcnt lgkmcnt(5)
	v_mfma_f32_16x16x32_bf16 v[148:151], v[220:223], v[148:151], v[124:127]
	s_waitcnt lgkmcnt(3)
	v_mfma_f32_16x16x32_bf16 v[124:127], v[228:231], v[224:227], v[56:59]
	s_waitcnt lgkmcnt(1)
	v_mfma_f32_16x16x32_bf16 v[120:123], v[236:239], v[224:227], v[116:119]
	v_mfma_f32_16x16x32_bf16 v[116:119], v[232:235], v[224:227], v[208:211]
	s_waitcnt lgkmcnt(0)
	v_mfma_f32_16x16x32_bf16 v[56:59], v[240:243], v[224:227], v[148:151]
	s_setprio 0
	s_add_i32 s6, s34, -3
	s_add_i32 s17, s35, 3
	s_and_b64 s[0:1], s[36:37], exec
	s_cselect_b32 s0, s6, s17
	s_or_b32 s0, s0, s31
	s_ashr_i32 s1, s0, 31
	s_lshl_b64 s[0:1], s[0:1], 15
	v_lshl_add_u64 v[136:137], v[134:135], 0, s[0:1]
	v_cvt_pk_bf16_f32 v144, v124, v125
	v_cvt_pk_bf16_f32 v145, v126, v127
	s_waitcnt lgkmcnt(0)
	s_barrier
	global_store_dwordx2 v[136:137], v[144:145], off
	v_cvt_pk_bf16_f32 v144, v120, v121
	v_cvt_pk_bf16_f32 v145, v122, v123
	global_store_dwordx2 v[136:137], v[144:145], off offset:32
	v_cvt_pk_bf16_f32 v144, v116, v117
	v_cvt_pk_bf16_f32 v145, v118, v119
	global_store_dwordx2 v[136:137], v[144:145], off offset:64
	v_cvt_pk_bf16_f32 v144, v56, v57
	v_cvt_pk_bf16_f32 v145, v58, v59
	global_store_dwordx2 v[136:137], v[144:145], off offset:96
	ds_read_b128 v[208:211], v192 offset:52224
	ds_read_b128 v[212:215], v193 offset:56576
	ds_read_b128 v[216:219], v192 offset:60928
	ds_read_b128 v[220:223], v193 offset:65280
	ds_read_b128 v[228:231], v195 offset:52224
	ds_read_b128 v[232:235], v196 offset:56576
	ds_read_b128 v[236:239], v195 offset:60928
	ds_read_b128 v[240:243], v196 offset:65280
	s_waitcnt vmcnt(18)
	v_lshlrev_b32_e32 v145, 16, v72
	v_lshlrev_b32_e32 v144, 16, v64
	s_waitcnt vmcnt(14)
	v_mov_b32_e32 v148, v88
	s_waitcnt vmcnt(10)
	v_mov_b32_e32 v149, v104
	v_mov_b32_e32 v150, v96
	s_waitcnt vmcnt(8)
	v_mov_b32_e32 v151, v112
	v_lshlrev_b32_e32 v137, 16, v68
	v_lshlrev_b32_e32 v136, 16, v60
	v_pk_mul_f32 v[152:153], v[150:151], v[144:145]
	v_pk_mul_f32 v[144:145], v[148:149], v[144:145]
	v_pk_fma_f32 v[152:153], v[148:149], v[136:137], v[152:153] neg_lo:[0,0,1] neg_hi:[0,0,1]
	v_pk_fma_f32 v[136:137], v[150:151], v[136:137], v[144:145]
	v_and_b32_e32 v145, 0xffff0000, v72
	v_cvt_pk_bf16_f32 v143, v136, v137
	v_lshlrev_b32_e32 v137, 16, v80
	v_lshlrev_b32_e32 v136, 16, v76
	v_pk_mul_f32 v[136:137], v[170:171], v[136:137]
	v_and_b32_e32 v144, 0xffff0000, v64
	v_mov_b32_e32 v148, v89
	v_mov_b32_e32 v149, v105
	v_mov_b32_e32 v150, v97
	v_mov_b32_e32 v151, v113
	v_cvt_pk_bf16_f32 v141, v152, v153
	v_cvt_pk_bf16_f32 v147, v136, v137
	v_and_b32_e32 v137, 0xffff0000, v68
	v_and_b32_e32 v136, 0xffff0000, v60
	v_pk_mul_f32 v[152:153], v[150:151], v[144:145]
	v_pk_mul_f32 v[144:145], v[148:149], v[144:145]
	v_pk_fma_f32 v[152:153], v[148:149], v[136:137], v[152:153] neg_lo:[0,0,1] neg_hi:[0,0,1]
	v_pk_fma_f32 v[136:137], v[150:151], v[136:137], v[144:145]
	v_cvt_pk_bf16_f32 v152, v152, v153
	v_cvt_pk_bf16_f32 v136, v136, v137
	ds_write2_b32 v146, v143, v136 offset1:68
	v_and_b32_e32 v137, 0xffff0000, v80
	v_and_b32_e32 v136, 0xffff0000, v76
	v_pk_mul_f32 v[136:137], v[170:171], v[136:137]
	v_lshlrev_b32_e32 v145, 16, v73
	v_cvt_pk_bf16_f32 v136, v136, v137
	v_lshlrev_b32_e32 v144, 16, v65
	v_mov_b32_e32 v148, v90
	v_mov_b32_e32 v149, v106
	v_mov_b32_e32 v150, v98
	v_mov_b32_e32 v151, v114
	ds_write2_b32 v187, v141, v152 offset1:68
	ds_write2_b32 v138, v147, v136 offset1:68
	v_lshlrev_b32_e32 v137, 16, v69
	v_lshlrev_b32_e32 v136, 16, v61
	v_pk_mul_f32 v[152:153], v[150:151], v[144:145]
	v_pk_mul_f32 v[144:145], v[148:149], v[144:145]
	v_pk_fma_f32 v[152:153], v[148:149], v[136:137], v[152:153] neg_lo:[0,0,1] neg_hi:[0,0,1]
	v_pk_fma_f32 v[136:137], v[150:151], v[136:137], v[144:145]
	v_and_b32_e32 v145, 0xffff0000, v73
	v_cvt_pk_bf16_f32 v143, v136, v137
	v_lshlrev_b32_e32 v137, 16, v81
	v_lshlrev_b32_e32 v136, 16, v77
	v_pk_mul_f32 v[136:137], v[170:171], v[136:137]
	v_and_b32_e32 v144, 0xffff0000, v65
	v_mov_b32_e32 v148, v91
	v_mov_b32_e32 v149, v107
	v_mov_b32_e32 v150, v99
	v_mov_b32_e32 v151, v115
	v_cvt_pk_bf16_f32 v141, v152, v153
	v_cvt_pk_bf16_f32 v147, v136, v137
	v_and_b32_e32 v137, 0xffff0000, v69
	v_and_b32_e32 v136, 0xffff0000, v61
	v_pk_mul_f32 v[152:153], v[150:151], v[144:145]
	v_pk_mul_f32 v[144:145], v[148:149], v[144:145]
	v_pk_fma_f32 v[152:153], v[148:149], v[136:137], v[152:153] neg_lo:[0,0,1] neg_hi:[0,0,1]
	v_pk_fma_f32 v[136:137], v[150:151], v[136:137], v[144:145]
	v_cvt_pk_bf16_f32 v152, v152, v153
	v_cvt_pk_bf16_f32 v136, v136, v137
	ds_write2_b32 v146, v143, v136 offset0:136 offset1:204
	v_and_b32_e32 v137, 0xffff0000, v81
	v_and_b32_e32 v136, 0xffff0000, v77
	v_pk_mul_f32 v[136:137], v[170:171], v[136:137]
	v_lshlrev_b32_e32 v145, 16, v74
	v_cvt_pk_bf16_f32 v136, v136, v137
	v_lshlrev_b32_e32 v144, 16, v66
	v_mov_b32_e32 v148, v84
	v_mov_b32_e32 v149, v100
	v_mov_b32_e32 v150, v92
	v_mov_b32_e32 v151, v108
	ds_write2_b32 v187, v141, v152 offset0:136 offset1:204
	ds_write2_b32 v138, v147, v136 offset0:136 offset1:204
	v_lshlrev_b32_e32 v137, 16, v70
	v_lshlrev_b32_e32 v136, 16, v62
	v_pk_mul_f32 v[152:153], v[150:151], v[144:145]
	v_pk_mul_f32 v[144:145], v[148:149], v[144:145]
	v_pk_fma_f32 v[152:153], v[148:149], v[136:137], v[152:153] neg_lo:[0,0,1] neg_hi:[0,0,1]
	v_pk_fma_f32 v[136:137], v[150:151], v[136:137], v[144:145]
	v_and_b32_e32 v145, 0xffff0000, v74
	v_cvt_pk_bf16_f32 v143, v136, v137
	v_lshlrev_b32_e32 v137, 16, v82
	v_lshlrev_b32_e32 v136, 16, v78
	v_pk_mul_f32 v[136:137], v[170:171], v[136:137]
	v_and_b32_e32 v144, 0xffff0000, v66
	v_mov_b32_e32 v148, v85
	v_mov_b32_e32 v149, v101
	v_mov_b32_e32 v150, v93
	v_mov_b32_e32 v151, v109
	v_cvt_pk_bf16_f32 v141, v152, v153
	v_cvt_pk_bf16_f32 v147, v136, v137
	v_and_b32_e32 v137, 0xffff0000, v70
	v_and_b32_e32 v136, 0xffff0000, v62
	v_pk_mul_f32 v[152:153], v[150:151], v[144:145]
	v_pk_mul_f32 v[144:145], v[148:149], v[144:145]
	v_pk_fma_f32 v[152:153], v[148:149], v[136:137], v[152:153] neg_lo:[0,0,1] neg_hi:[0,0,1]
	v_pk_fma_f32 v[136:137], v[150:151], v[136:137], v[144:145]
	v_cvt_pk_bf16_f32 v152, v152, v153
	v_cvt_pk_bf16_f32 v136, v136, v137
	ds_write2_b32 v142, v143, v136 offset0:16 offset1:84
	v_and_b32_e32 v137, 0xffff0000, v82
	v_and_b32_e32 v136, 0xffff0000, v78
	v_pk_mul_f32 v[136:137], v[170:171], v[136:137]
	v_lshlrev_b32_e32 v145, 16, v75
	v_cvt_pk_bf16_f32 v136, v136, v137
	v_lshlrev_b32_e32 v144, 16, v67
	v_mov_b32_e32 v148, v86
	v_mov_b32_e32 v149, v102
	v_mov_b32_e32 v150, v94
	v_mov_b32_e32 v151, v110
	ds_write2_b32 v139, v141, v152 offset0:16 offset1:84
	ds_write2_b32 v140, v147, v136 offset0:16 offset1:84
	v_lshlrev_b32_e32 v137, 16, v71
	v_lshlrev_b32_e32 v136, 16, v63
	v_pk_mul_f32 v[152:153], v[150:151], v[144:145]
	v_pk_mul_f32 v[144:145], v[148:149], v[144:145]
	v_pk_fma_f32 v[152:153], v[148:149], v[136:137], v[152:153] neg_lo:[0,0,1] neg_hi:[0,0,1]
	v_pk_fma_f32 v[136:137], v[150:151], v[136:137], v[144:145]
	v_and_b32_e32 v145, 0xffff0000, v75
	v_cvt_pk_bf16_f32 v143, v136, v137
	v_lshlrev_b32_e32 v137, 16, v83
	v_lshlrev_b32_e32 v136, 16, v79
	v_pk_mul_f32 v[136:137], v[170:171], v[136:137]
	v_and_b32_e32 v144, 0xffff0000, v67
	v_mov_b32_e32 v148, v87
	v_mov_b32_e32 v149, v103
	v_mov_b32_e32 v150, v95
	v_mov_b32_e32 v151, v111
	v_cvt_pk_bf16_f32 v141, v152, v153
	v_cvt_pk_bf16_f32 v147, v136, v137
	v_and_b32_e32 v137, 0xffff0000, v71
	v_and_b32_e32 v136, 0xffff0000, v63
	v_pk_mul_f32 v[152:153], v[150:151], v[144:145]
	v_pk_mul_f32 v[144:145], v[148:149], v[144:145]
	v_pk_fma_f32 v[152:153], v[148:149], v[136:137], v[152:153] neg_lo:[0,0,1] neg_hi:[0,0,1]
	v_pk_fma_f32 v[136:137], v[150:151], v[136:137], v[144:145]
	v_cvt_pk_bf16_f32 v152, v152, v153
	v_cvt_pk_bf16_f32 v136, v136, v137
	ds_write2_b32 v142, v143, v136 offset0:152 offset1:220
	v_and_b32_e32 v137, 0xffff0000, v83
	v_and_b32_e32 v136, 0xffff0000, v79
	v_pk_mul_f32 v[136:137], v[170:171], v[136:137]
	s_cmp_gt_u32 s38, 26
	v_cvt_pk_bf16_f32 v136, v136, v137
	ds_write2_b32 v139, v141, v152 offset0:152 offset1:220
	ds_write2_b32 v140, v147, v136 offset0:152 offset1:220
	ds_read_b128 v[148:151], v203
	ds_read_b128 v[224:227], v204
	s_cbranch_scc1 .LBB0_200
	s_and_b64 s[0:1], s[36:37], exec
	s_cselect_b32 s0, s34, s35
	v_lshl_add_u32 v84, s0, 7, v183
	v_add_u32_e32 v62, s29, v84
	v_mov_b64_e32 v[60:61], s[14:15]
	v_mad_i64_i32 v[76:77], s[0:1], v62, s59, v[60:61]
	v_lshl_add_u64 v[68:69], v[76:77], 0, v[154:155]
	s_lshl_b32 s6, s30, 1
	v_add_co_u32_e32 v72, vcc, 0x2000, v68
	v_lshl_add_u64 v[76:77], v[76:77], 0, s[6:7]
	v_lshlrev_b32_e32 v84, 6, v84
	v_addc_co_u32_e32 v73, vcc, 0, v69, vcc
	v_lshl_add_u64 v[76:77], v[76:77], 0, v[154:155]
	v_ashrrev_i32_e32 v85, 31, v84
	v_add_co_u32_e32 v80, vcc, 0x2000, v76
	v_lshlrev_b64 v[84:85], 2, v[84:85]
	s_nop 0
	v_addc_co_u32_e32 v81, vcc, 0, v77, vcc
	v_lshl_add_u64 v[104:105], v[160:161], 0, v[84:85]
	v_lshl_add_u64 v[112:113], v[162:163], 0, v[84:85]
	global_load_dwordx4 v[60:63], v[68:69], off offset:1536
	global_load_dwordx4 v[64:67], v[68:69], off offset:1664
	s_nop 0
	global_load_dwordx4 v[68:71], v[72:73], off
	s_nop 0
	global_load_dwordx4 v[72:75], v[72:73], off offset:128
	s_nop 0
	global_load_dwordx4 v[76:79], v[76:77], off offset:3072
	s_nop 0
	global_load_dwordx4 v[80:83], v[80:81], off offset:1536
	s_nop 0
	global_load_dwordx4 v[84:87], v[104:105], off offset:16
	global_load_dwordx4 v[88:91], v[104:105], off
	global_load_dwordx4 v[92:95], v[112:113], off offset:16
	global_load_dwordx4 v[96:99], v[112:113], off
	global_load_dwordx4 v[100:103], v[104:105], off offset:272
	s_nop 0
	global_load_dwordx4 v[104:107], v[104:105], off offset:256
	s_nop 0
	global_load_dwordx4 v[108:111], v[112:113], off offset:272
	s_nop 0
	global_load_dwordx4 v[112:115], v[112:113], off offset:256
	s_branch .LBB0_200
